# v35 + norm_rows / prologue x-norm: early vmcnt waits inside the row-load burst moved after the last load (all 32/16 loads of a row issued back to back)
# speedup vs baseline: 1.0080x; 1.0080x over previous
.LBB0_47:
	v_mov_b32_e32 v52, v56
	s_add_u32 s4, s12, s6
	s_addc_u32 s5, s13, s7
	v_ashrrev_i32_e32 v53, 31, v52
	v_lshl_add_u64 v[4:5], v[52:53], 4, s[4:5]
	global_load_dwordx4 v[60:63], v[4:5], off
	global_load_dwordx4 v[64:67], v[4:5], off offset:1024
	global_load_dwordx4 v[68:71], v[4:5], off offset:2048
	global_load_dwordx4 v[44:47], v[4:5], off offset:3072
	v_add_co_u32_e32 v0, vcc, s14, v4
	s_mov_b64 s[4:5], vcc
	v_add_co_u32_e32 v6, vcc, s15, v4
	s_load_dwordx4 s[20:23], s[0:1], 0xa0
	s_nop 0
	v_addc_co_u32_e32 v7, vcc, 0, v5, vcc
	global_load_dwordx4 v[48:51], v[6:7], off offset:-4096
	v_addc_co_u32_e64 v1, vcc, 0, v5, s[4:5]
	global_load_dwordx4 v[40:43], v[0:1], off offset:1024
	global_load_dwordx4 v[36:39], v[0:1], off offset:2048
	global_load_dwordx4 v[32:35], v[0:1], off offset:3072
	global_load_dwordx4 v[28:31], v[6:7], off
	s_nop 0
	global_load_dwordx4 v[0:3], v[6:7], off offset:1024
	s_waitcnt lgkmcnt(0)
	s_add_u32 s4, s22, s2
	s_addc_u32 s5, s23, s3
	global_load_dwordx4 v[24:27], v[6:7], off offset:2048
	global_load_dwordx4 v[20:23], v[6:7], off offset:3072
	v_lshl_add_u64 v[8:9], v[52:53], 3, s[4:5]
	v_add_co_u32_e32 v72, vcc, s17, v8
	s_nop 1
	v_addc_co_u32_e32 v73, vcc, 0, v9, vcc
	v_add_co_u32_e32 v54, vcc, s18, v8
	s_nop 1
	v_addc_co_u32_e32 v55, vcc, 0, v9, vcc
	v_add_co_u32_e32 v4, vcc, s16, v4
	s_nop 1
	v_addc_co_u32_e32 v5, vcc, 0, v5, vcc
	global_load_dwordx4 v[16:19], v[4:5], off
	global_load_dwordx4 v[12:15], v[4:5], off offset:1024
	global_load_dwordx4 v[8:11], v[4:5], off offset:2048
	s_nop 0
	global_load_dwordx4 v[4:7], v[4:5], off offset:3072
	s_waitcnt vmcnt(15)
	v_mul_f32_e32 v53, v61, v61
	s_waitcnt vmcnt(14)
	v_mul_f32_e32 v76, v65, v65
	v_mul_f32_e32 v77, v67, v67
	v_cvt_pk_bf16_f32 v74, v60, v61
	v_cvt_pk_bf16_f32 v75, v62, v63
	v_mul_f32_e32 v63, v63, v63
	s_waitcnt vmcnt(13)
	v_mul_f32_e32 v78, v69, v69
	v_mul_f32_e32 v79, v71, v71
	s_waitcnt vmcnt(12)
	v_mul_f32_e32 v80, v45, v45
	global_store_dwordx2 v[54:55], v[74:75], off offset:-4096
	v_cvt_pk_bf16_f32 v74, v64, v65
	v_cvt_pk_bf16_f32 v75, v66, v67
	v_fmac_f32_e32 v53, v60, v60
	v_fmac_f32_e32 v63, v62, v62
	v_fmac_f32_e32 v76, v64, v64
	v_fmac_f32_e32 v77, v66, v66
	global_store_dwordx2 v[72:73], v[74:75], off offset:512
	v_cvt_pk_bf16_f32 v60, v68, v69
	v_fmac_f32_e32 v78, v68, v68
	v_fmac_f32_e32 v79, v70, v70
	v_cvt_pk_bf16_f32 v61, v70, v71
	v_add_f32_e32 v53, v53, v63
	v_add_f32_e32 v62, v76, v77
	global_store_dwordx2 v[72:73], v[60:61], off offset:1024
	v_cvt_pk_bf16_f32 v60, v44, v45
	v_fmac_f32_e32 v80, v44, v44
	v_mul_f32_e32 v44, v47, v47
	v_add_f32_e32 v63, v78, v79
	v_add_f32_e32 v45, v53, v62
	v_fmac_f32_e32 v44, v46, v46
	v_cvt_pk_bf16_f32 v61, v46, v47
	global_store_dwordx2 v[72:73], v[60:61], off offset:1536
	s_waitcnt vmcnt(15)
	v_cvt_pk_bf16_f32 v60, v48, v49
	v_add_f32_e32 v45, v45, v63
	v_add_f32_e32 v44, v80, v44
	v_cvt_pk_bf16_f32 v61, v50, v51
	global_store_dwordx2 v[72:73], v[60:61], off offset:2048
	s_waitcnt vmcnt(15)
	v_cvt_pk_bf16_f32 v60, v40, v41
	v_add_f32_e32 v44, v45, v44
	v_mul_f32_e32 v45, v49, v49
	v_mul_f32_e32 v46, v51, v51
	v_mul_f32_e32 v41, v41, v41
	v_cvt_pk_bf16_f32 v61, v42, v43
	global_store_dwordx2 v[72:73], v[60:61], off offset:2560
	s_waitcnt vmcnt(15)
	v_cvt_pk_bf16_f32 v60, v36, v37
	v_fmac_f32_e32 v45, v48, v48
	v_fmac_f32_e32 v46, v50, v50
	v_fmac_f32_e32 v41, v40, v40
	v_mul_f32_e32 v40, v43, v43
	v_mul_f32_e32 v37, v37, v37
	v_cvt_pk_bf16_f32 v61, v38, v39
	global_store_dwordx2 v[72:73], v[60:61], off offset:3072
	s_waitcnt vmcnt(15)
	v_cvt_pk_bf16_f32 v60, v32, v33
	v_add_f32_e32 v45, v45, v46
	v_fmac_f32_e32 v40, v42, v42
	v_fmac_f32_e32 v37, v36, v36
	v_mul_f32_e32 v36, v39, v39
	v_mul_f32_e32 v33, v33, v33
	v_cvt_pk_bf16_f32 v61, v34, v35
	global_store_dwordx2 v[72:73], v[60:61], off offset:3584
	s_waitcnt vmcnt(15)
	v_cvt_pk_bf16_f32 v60, v28, v29
	v_add_f32_e32 v44, v44, v45
	v_add_f32_e32 v40, v41, v40
	v_fmac_f32_e32 v36, v38, v38
	v_fmac_f32_e32 v33, v32, v32
	v_mul_f32_e32 v32, v35, v35
	v_mul_f32_e32 v29, v29, v29
	v_cvt_pk_bf16_f32 v61, v30, v31
	global_store_dwordx2 v[54:55], v[60:61], off
	s_waitcnt vmcnt(15)
	v_cvt_pk_bf16_f32 v60, v0, v1
	v_add_f32_e32 v40, v44, v40
	v_add_f32_e32 v36, v37, v36
	v_fmac_f32_e32 v32, v34, v34
	v_fmac_f32_e32 v29, v28, v28
	v_mul_f32_e32 v28, v31, v31
	v_mul_f32_e32 v1, v1, v1
	v_add_f32_e32 v36, v40, v36
	v_add_f32_e32 v32, v33, v32
	v_fmac_f32_e32 v28, v30, v30
	v_fmac_f32_e32 v1, v0, v0
	v_mul_f32_e32 v0, v3, v3
	v_add_f32_e32 v32, v36, v32
	v_add_f32_e32 v28, v29, v28
	v_fmac_f32_e32 v0, v2, v2
	v_add_f32_e32 v28, v32, v28
	v_add_f32_e32 v0, v1, v0
	v_add_f32_e32 v0, v28, v0
	s_waitcnt vmcnt(14)
	v_mul_f32_e32 v1, v25, v25
	v_mul_f32_e32 v28, v27, v27
	v_fmac_f32_e32 v1, v24, v24
	v_fmac_f32_e32 v28, v26, v26
	v_add_f32_e32 v1, v1, v28
	v_add_f32_e32 v0, v0, v1
	s_waitcnt vmcnt(13)
	v_mul_f32_e32 v1, v21, v21
	v_mul_f32_e32 v28, v23, v23
	v_fmac_f32_e32 v1, v20, v20
	v_fmac_f32_e32 v28, v22, v22
	v_add_f32_e32 v1, v1, v28
	v_add_f32_e32 v0, v0, v1
	s_waitcnt vmcnt(12)
	v_mul_f32_e32 v1, v17, v17
	v_mul_f32_e32 v28, v19, v19
	v_fmac_f32_e32 v1, v16, v16
	v_fmac_f32_e32 v28, v18, v18
	v_add_f32_e32 v1, v1, v28
	v_add_f32_e32 v0, v0, v1
	s_waitcnt vmcnt(11)
	v_mul_f32_e32 v1, v13, v13
	v_mul_f32_e32 v28, v15, v15
	v_fmac_f32_e32 v1, v12, v12
	v_fmac_f32_e32 v28, v14, v14
	v_add_f32_e32 v1, v1, v28
	v_add_f32_e32 v0, v0, v1
	s_waitcnt vmcnt(10)
	v_mul_f32_e32 v1, v9, v9
	v_mul_f32_e32 v28, v11, v11
	v_fmac_f32_e32 v1, v8, v8
	v_fmac_f32_e32 v28, v10, v10
	v_add_f32_e32 v1, v1, v28
	v_add_f32_e32 v0, v0, v1
	s_waitcnt vmcnt(9)
	v_mul_f32_e32 v1, v5, v5
	v_mul_f32_e32 v28, v7, v7
	v_fmac_f32_e32 v1, v4, v4
	v_fmac_f32_e32 v28, v6, v6
	v_add_f32_e32 v1, v1, v28
	v_add_f32_e32 v28, v0, v1
	ds_swizzle_b32 v29, v28 offset:swizzle(SWAP,1)
	v_cvt_pk_bf16_f32 v61, v2, v3
	global_store_dwordx2 v[54:55], v[60:61], off offset:512
	v_cvt_pk_bf16_f32 v0, v24, v25
	v_cvt_pk_bf16_f32 v1, v26, v27
	s_waitcnt lgkmcnt(0)
	v_add_f32_e32 v2, v28, v29
	ds_swizzle_b32 v3, v2 offset:swizzle(SWAP,2)
	global_store_dwordx2 v[54:55], v[0:1], off offset:1024
	v_cvt_pk_bf16_f32 v0, v20, v21
	v_cvt_pk_bf16_f32 v1, v22, v23
	global_store_dwordx2 v[54:55], v[0:1], off offset:1536
	s_waitcnt lgkmcnt(0)
	v_add_f32_e32 v2, v2, v3
	ds_swizzle_b32 v3, v2 offset:swizzle(SWAP,4)
	v_cvt_pk_bf16_f32 v0, v16, v17
	v_cvt_pk_bf16_f32 v1, v18, v19
	global_store_dwordx2 v[54:55], v[0:1], off offset:2048
	v_cvt_pk_bf16_f32 v0, v12, v13
	s_waitcnt lgkmcnt(0)
	v_add_f32_e32 v2, v2, v3
	ds_swizzle_b32 v3, v2 offset:swizzle(SWAP,8)
	v_cvt_pk_bf16_f32 v1, v14, v15
	global_store_dwordx2 v[54:55], v[0:1], off offset:2560
	v_cvt_pk_bf16_f32 v0, v8, v9
	v_cvt_pk_bf16_f32 v1, v10, v11
	s_waitcnt lgkmcnt(0)
	v_add_f32_e32 v2, v2, v3
	ds_swizzle_b32 v3, v2 offset:swizzle(SWAP,16)
	global_store_dwordx2 v[54:55], v[0:1], off offset:3072
	v_cvt_pk_bf16_f32 v0, v4, v5
	v_cvt_pk_bf16_f32 v1, v6, v7
	global_store_dwordx2 v[54:55], v[0:1], off offset:3584
	s_waitcnt lgkmcnt(0)
	v_add_f32_e32 v0, v2, v3
	v_cmp_eq_u32_e32 vcc, 0, v52
	v_readlane_b32 s4, v0, 0
	v_readlane_b32 s5, v0, 32
	s_and_saveexec_b64 s[8:9], vcc
	s_cbranch_execz .LBB0_46
	v_mov_b32_e32 v0, s5
	v_add_f32_e32 v0, s4, v0
	v_fmamk_f32 v0, v0, 0x39800000, v57
	v_mul_f32_e32 v1, 0x4f800000, v0
	v_cmp_gt_f32_e32 vcc, s19, v0
	s_load_dwordx4 s[20:23], s[0:1], 0xa0
	s_nop 0
	v_cndmask_b32_e32 v0, v0, v1, vcc
	v_sqrt_f32_e32 v1, v0
	s_nop 0
	v_add_u32_e32 v2, -1, v1
	v_fma_f32 v4, -v2, v1, v0
	v_add_u32_e32 v3, 1, v1
	v_cmp_ge_f32_e64 s[4:5], 0, v4
	s_nop 1
	v_cndmask_b32_e64 v2, v1, v2, s[4:5]
	v_fma_f32 v1, -v3, v1, v0
	v_cmp_lt_f32_e64 s[4:5], 0, v1
	s_nop 1
	v_cndmask_b32_e64 v1, v2, v3, s[4:5]
	v_mul_f32_e32 v2, 0x37800000, v1
	v_cndmask_b32_e32 v1, v1, v2, vcc
	v_cmp_class_f32_e32 vcc, v0, v58
	s_nop 1
	v_cndmask_b32_e32 v0, v1, v0, vcc
	v_div_scale_f32 v1, s[4:5], v0, v0, 1.0
	v_rcp_f32_e32 v2, v1
	s_waitcnt lgkmcnt(0)
	s_add_u32 s4, s22, s10
	s_addc_u32 s5, s23, s11
	v_fma_f32 v3, -v1, v2, 1.0
	v_fmac_f32_e32 v2, v3, v2
	v_div_scale_f32 v3, vcc, 1.0, v0, 1.0
	v_mul_f32_e32 v4, v3, v2
	v_fma_f32 v5, -v1, v4, v3
	v_fmac_f32_e32 v4, v5, v2
	v_fma_f32 v1, -v1, v4, v3
	v_div_fmas_f32 v1, v1, v2, v4
	v_div_fixup_f32 v0, v1, v0, 1.0
	global_store_dword v59, v0, s[4:5]
	s_branch .LBB0_46

.LBB0_805:
	v_readlane_b32 s16, v252, 0
	v_readlane_b32 s18, v252, 2
	v_mov_b32_e32 v66, v202
	v_readlane_b32 s19, v252, 3
	s_add_u32 s0, s18, s2
	s_addc_u32 s1, s19, s3
	v_ashrrev_i32_e32 v67, 31, v66
	v_lshl_add_u64 v[72:73], v[66:67], 3, s[0:1]
	v_add_co_u32_e32 v70, vcc, 0x44700000, v72
	v_readlane_b32 s17, v252, 1
	s_nop 0
	v_addc_co_u32_e32 v71, vcc, 0, v73, vcc
	v_add_co_u32_e32 v68, vcc, 0x44701000, v72
	global_load_dwordx2 v[74:75], v[70:71], off
	global_load_dwordx2 v[76:77], v[70:71], off offset:512
	global_load_dwordx2 v[78:79], v[70:71], off offset:1024
	global_load_dwordx2 v[80:81], v[70:71], off offset:1536
	global_load_dwordx2 v[82:83], v[70:71], off offset:2048
	global_load_dwordx2 v[84:85], v[70:71], off offset:2560
	global_load_dwordx2 v[124:125], v[70:71], off offset:3072
	v_addc_co_u32_e32 v69, vcc, 0, v73, vcc
	global_load_dwordx2 v[126:127], v[70:71], off offset:3584
	global_load_dwordx2 v[128:129], v[68:69], off
	global_load_dwordx2 v[120:121], v[68:69], off offset:512
	v_add_co_u32_e32 v86, vcc, 0x3a200000, v72
	s_nop 1
	v_addc_co_u32_e32 v87, vcc, 0, v73, vcc
	global_load_dwordx2 v[130:131], v[86:87], off
	global_load_dwordx2 v[132:133], v[86:87], off offset:512
	global_load_dwordx2 v[122:123], v[68:69], off offset:1024
	global_load_dwordx2 v[118:119], v[68:69], off offset:1536
	global_load_dwordx2 v[134:135], v[86:87], off offset:1024
	global_load_dwordx2 v[116:117], v[68:69], off offset:2048
	global_load_dwordx2 v[114:115], v[68:69], off offset:2560
	global_load_dwordx2 v[102:103], v[68:69], off offset:3072
	global_load_dwordx2 v[98:99], v[68:69], off offset:3584
	global_load_dwordx2 v[136:137], v[86:87], off offset:1536
	global_load_dwordx2 v[138:139], v[86:87], off offset:2048
	global_load_dwordx2 v[140:141], v[86:87], off offset:2560
	global_load_dwordx2 v[142:143], v[86:87], off offset:3072
	global_load_dwordx2 v[144:145], v[86:87], off offset:3584
	v_add_co_u32_e32 v72, vcc, 0x3a201000, v72
	s_nop 1
	v_addc_co_u32_e32 v73, vcc, 0, v73, vcc
	global_load_dwordx2 v[146:147], v[72:73], off
	global_load_dwordx2 v[148:149], v[72:73], off offset:512
	global_load_dwordx2 v[198:199], v[72:73], off offset:1024
	global_load_dwordx2 v[200:201], v[72:73], off offset:1536
	global_load_dwordx2 v[204:205], v[72:73], off offset:2048
	global_load_dwordx2 v[206:207], v[72:73], off offset:2560
	global_load_dwordx2 v[208:209], v[72:73], off offset:3072
	global_load_dwordx2 v[218:219], v[72:73], off offset:3584
	s_waitcnt vmcnt(22)
	v_lshlrev_b32_e32 v110, 16, v74
	v_lshlrev_b32_e32 v94, 16, v80
	v_lshlrev_b32_e32 v72, 16, v120
	v_and_b32_e32 v73, 0xffff0000, v120
	v_and_b32_e32 v95, 0xffff0000, v80
	v_lshlrev_b32_e32 v96, 16, v81
	v_and_b32_e32 v97, 0xffff0000, v81
	v_lshlrev_b32_e32 v80, 16, v127
	v_and_b32_e32 v81, 0xffff0000, v127
	v_lshlrev_b32_e32 v100, 16, v78
	v_and_b32_e32 v101, 0xffff0000, v78
	v_lshlrev_b32_e32 v106, 16, v79
	v_and_b32_e32 v107, 0xffff0000, v79
	v_lshlrev_b32_e32 v78, 16, v126
	v_and_b32_e32 v79, 0xffff0000, v126
	v_lshlrev_b32_e32 v108, 16, v76
	v_and_b32_e32 v109, 0xffff0000, v76
	v_lshlrev_b32_e32 v104, 16, v77
	v_and_b32_e32 v105, 0xffff0000, v77
	v_lshlrev_b32_e32 v86, 16, v84
	v_and_b32_e32 v87, 0xffff0000, v84
	v_lshlrev_b32_e32 v88, 16, v85
	v_and_b32_e32 v89, 0xffff0000, v85
	v_lshlrev_b32_e32 v84, 16, v125
	v_and_b32_e32 v85, 0xffff0000, v125
	v_lshlrev_b32_e32 v76, 16, v129
	v_and_b32_e32 v77, 0xffff0000, v129
	v_and_b32_e32 v111, 0xffff0000, v74
	v_lshlrev_b32_e32 v112, 16, v75
	v_and_b32_e32 v113, 0xffff0000, v75
	v_lshlrev_b32_e32 v90, 16, v82
	v_and_b32_e32 v91, 0xffff0000, v82
	v_lshlrev_b32_e32 v92, 16, v83
	v_and_b32_e32 v93, 0xffff0000, v83
	v_lshlrev_b32_e32 v82, 16, v124
	v_and_b32_e32 v83, 0xffff0000, v124
	v_lshlrev_b32_e32 v74, 16, v128
	v_and_b32_e32 v75, 0xffff0000, v128
	s_waitcnt vmcnt(21)
	v_and_b32_e32 v197, 0xffff0000, v130
	v_and_b32_e32 v195, 0xffff0000, v131
	v_lshlrev_b32_e32 v196, 16, v130
	v_lshlrev_b32_e32 v194, 16, v131
	v_mul_f32_e32 v0, v197, v197
	v_mul_f32_e32 v67, v195, v195
	v_fmac_f32_e32 v0, v196, v196
	v_fmac_f32_e32 v67, v194, v194
	s_waitcnt vmcnt(20)
	v_and_b32_e32 v193, 0xffff0000, v132
	v_and_b32_e32 v191, 0xffff0000, v133
	v_add_f32_e32 v0, v0, v67
	v_lshlrev_b32_e32 v192, 16, v132
	v_lshlrev_b32_e32 v190, 16, v133
	v_mul_f32_e32 v67, v193, v193
	v_mul_f32_e32 v120, v191, v191
	v_fmac_f32_e32 v67, v192, v192
	v_fmac_f32_e32 v120, v190, v190
	v_add_f32_e32 v67, v67, v120
	s_waitcnt vmcnt(17)
	v_and_b32_e32 v189, 0xffff0000, v134
	v_and_b32_e32 v187, 0xffff0000, v135
	v_add_f32_e32 v0, v0, v67
	v_lshlrev_b32_e32 v188, 16, v134
	v_lshlrev_b32_e32 v186, 16, v135
	v_mul_f32_e32 v67, v189, v189
	v_mul_f32_e32 v120, v187, v187
	v_fmac_f32_e32 v67, v188, v188
	v_fmac_f32_e32 v120, v186, v186
	v_add_f32_e32 v67, v67, v120
	s_waitcnt vmcnt(12)
	v_and_b32_e32 v185, 0xffff0000, v136
	v_and_b32_e32 v183, 0xffff0000, v137
	v_add_f32_e32 v0, v0, v67
	v_lshlrev_b32_e32 v184, 16, v136
	v_lshlrev_b32_e32 v182, 16, v137
	v_mul_f32_e32 v67, v185, v185
	v_mul_f32_e32 v120, v183, v183
	v_fmac_f32_e32 v67, v184, v184
	v_fmac_f32_e32 v120, v182, v182
	v_add_f32_e32 v67, v67, v120
	s_waitcnt vmcnt(11)
	v_and_b32_e32 v181, 0xffff0000, v138
	v_and_b32_e32 v169, 0xffff0000, v139
	v_add_f32_e32 v0, v0, v67
	v_lshlrev_b32_e32 v180, 16, v138
	v_lshlrev_b32_e32 v168, 16, v139
	v_mul_f32_e32 v67, v181, v181
	v_mul_f32_e32 v120, v169, v169
	v_fmac_f32_e32 v67, v180, v180
	v_fmac_f32_e32 v120, v168, v168
	v_add_f32_e32 v67, v67, v120
	s_waitcnt vmcnt(10)
	v_and_b32_e32 v167, 0xffff0000, v140
	v_and_b32_e32 v165, 0xffff0000, v141
	v_add_f32_e32 v0, v0, v67
	v_lshlrev_b32_e32 v166, 16, v140
	v_lshlrev_b32_e32 v164, 16, v141
	v_mul_f32_e32 v67, v167, v167
	v_mul_f32_e32 v120, v165, v165
	v_fmac_f32_e32 v67, v166, v166
	v_fmac_f32_e32 v120, v164, v164
	v_add_f32_e32 v67, v67, v120
	s_waitcnt vmcnt(9)
	v_and_b32_e32 v163, 0xffff0000, v142
	v_and_b32_e32 v161, 0xffff0000, v143
	v_add_f32_e32 v0, v0, v67
	v_lshlrev_b32_e32 v162, 16, v142
	v_lshlrev_b32_e32 v160, 16, v143
	v_mul_f32_e32 v67, v163, v163
	v_mul_f32_e32 v120, v161, v161
	v_fmac_f32_e32 v67, v162, v162
	v_fmac_f32_e32 v120, v160, v160
	v_add_f32_e32 v67, v67, v120
	s_waitcnt vmcnt(8)
	v_and_b32_e32 v159, 0xffff0000, v144
	v_and_b32_e32 v157, 0xffff0000, v145
	v_add_f32_e32 v0, v0, v67
	v_lshlrev_b32_e32 v158, 16, v144
	v_lshlrev_b32_e32 v156, 16, v145
	v_mul_f32_e32 v67, v159, v159
	v_mul_f32_e32 v120, v157, v157
	v_fmac_f32_e32 v67, v158, v158
	v_fmac_f32_e32 v120, v156, v156
	v_add_f32_e32 v67, v67, v120
	s_waitcnt vmcnt(7)
	v_and_b32_e32 v155, 0xffff0000, v146
	v_and_b32_e32 v127, 0xffff0000, v147
	v_add_f32_e32 v0, v0, v67
	v_lshlrev_b32_e32 v154, 16, v146
	v_lshlrev_b32_e32 v126, 16, v147
	v_mul_f32_e32 v67, v155, v155
	v_mul_f32_e32 v120, v127, v127
	v_fmac_f32_e32 v67, v154, v154
	v_fmac_f32_e32 v120, v126, v126
	v_add_f32_e32 v67, v67, v120
	s_waitcnt vmcnt(6)
	v_and_b32_e32 v153, 0xffff0000, v148
	v_and_b32_e32 v131, 0xffff0000, v149
	v_add_f32_e32 v0, v0, v67
	v_lshlrev_b32_e32 v152, 16, v148
	v_lshlrev_b32_e32 v130, 16, v149
	v_mul_f32_e32 v67, v153, v153
	v_mul_f32_e32 v120, v131, v131
	v_fmac_f32_e32 v67, v152, v152
	v_fmac_f32_e32 v120, v130, v130
	v_add_f32_e32 v67, v67, v120
	s_waitcnt vmcnt(5)
	v_and_b32_e32 v151, 0xffff0000, v198
	v_and_b32_e32 v149, 0xffff0000, v199
	v_add_f32_e32 v0, v0, v67
	v_lshlrev_b32_e32 v150, 16, v198
	v_lshlrev_b32_e32 v148, 16, v199
	v_mul_f32_e32 v67, v151, v151
	v_mul_f32_e32 v120, v149, v149
	v_fmac_f32_e32 v67, v150, v150
	v_fmac_f32_e32 v120, v148, v148
	v_add_f32_e32 v67, v67, v120
	s_waitcnt vmcnt(4)
	v_and_b32_e32 v147, 0xffff0000, v200
	v_and_b32_e32 v145, 0xffff0000, v201
	v_add_f32_e32 v0, v0, v67
	v_lshlrev_b32_e32 v146, 16, v200
	v_lshlrev_b32_e32 v144, 16, v201
	v_mul_f32_e32 v67, v147, v147
	v_mul_f32_e32 v120, v145, v145
	v_fmac_f32_e32 v67, v146, v146
	v_fmac_f32_e32 v120, v144, v144
	v_add_f32_e32 v67, v67, v120
	s_waitcnt vmcnt(3)
	v_and_b32_e32 v143, 0xffff0000, v204
	v_and_b32_e32 v141, 0xffff0000, v205
	v_add_f32_e32 v0, v0, v67
	v_lshlrev_b32_e32 v142, 16, v204
	v_lshlrev_b32_e32 v140, 16, v205
	v_mul_f32_e32 v67, v143, v143
	v_mul_f32_e32 v120, v141, v141
	v_fmac_f32_e32 v67, v142, v142
	v_fmac_f32_e32 v120, v140, v140
	v_add_f32_e32 v67, v67, v120
	s_waitcnt vmcnt(2)
	v_and_b32_e32 v139, 0xffff0000, v206
	v_and_b32_e32 v137, 0xffff0000, v207
	v_add_f32_e32 v0, v0, v67
	v_lshlrev_b32_e32 v138, 16, v206
	v_lshlrev_b32_e32 v136, 16, v207
	v_mul_f32_e32 v67, v139, v139
	v_mul_f32_e32 v120, v137, v137
	v_fmac_f32_e32 v67, v138, v138
	v_fmac_f32_e32 v120, v136, v136
	v_add_f32_e32 v67, v67, v120
	s_waitcnt vmcnt(1)
	v_and_b32_e32 v129, 0xffff0000, v208
	v_and_b32_e32 v125, 0xffff0000, v209
	v_add_f32_e32 v0, v0, v67
	v_lshlrev_b32_e32 v128, 16, v208
	v_lshlrev_b32_e32 v124, 16, v209
	v_mul_f32_e32 v67, v129, v129
	v_mul_f32_e32 v120, v125, v125
	v_fmac_f32_e32 v67, v128, v128
	v_fmac_f32_e32 v120, v124, v124
	v_add_f32_e32 v67, v67, v120
	s_waitcnt vmcnt(0)
	v_and_b32_e32 v135, 0xffff0000, v218
	v_and_b32_e32 v133, 0xffff0000, v219
	v_add_f32_e32 v0, v0, v67
	v_lshlrev_b32_e32 v134, 16, v218
	v_lshlrev_b32_e32 v132, 16, v219
	v_mul_f32_e32 v67, v135, v135
	v_mul_f32_e32 v120, v133, v133
	v_fmac_f32_e32 v67, v134, v134
	v_fmac_f32_e32 v120, v132, v132
	v_add_f32_e32 v67, v67, v120
	v_add_f32_e32 v0, v0, v67
	ds_swizzle_b32 v67, v0 offset:swizzle(SWAP,1)
	v_lshlrev_b32_e32 v198, 16, v102
	v_and_b32_e32 v199, 0xffff0000, v102
	v_lshlrev_b32_e32 v228, 16, v103
	v_and_b32_e32 v229, 0xffff0000, v103
	s_waitcnt lgkmcnt(0)
	v_add_f32_e32 v0, v0, v67
	ds_swizzle_b32 v67, v0 offset:swizzle(SWAP,2)
	v_lshlrev_b32_e32 v200, 16, v98
	v_and_b32_e32 v201, 0xffff0000, v98
	v_lshlrev_b32_e32 v230, 16, v99
	v_and_b32_e32 v231, 0xffff0000, v99
	s_waitcnt lgkmcnt(0)
	v_add_f32_e32 v0, v0, v67
	ds_swizzle_b32 v67, v0 offset:swizzle(SWAP,4)
	v_lshlrev_b32_e32 v224, 16, v114
	v_and_b32_e32 v225, 0xffff0000, v114
	v_lshlrev_b32_e32 v226, 16, v115
	v_and_b32_e32 v227, 0xffff0000, v115
	s_waitcnt lgkmcnt(0)
	v_add_f32_e32 v0, v0, v67
	ds_swizzle_b32 v67, v0 offset:swizzle(SWAP,8)
	v_lshlrev_b32_e32 v204, 16, v121
	v_and_b32_e32 v205, 0xffff0000, v121
	v_lshlrev_b32_e32 v220, 16, v116
	v_and_b32_e32 v221, 0xffff0000, v116
	s_waitcnt lgkmcnt(0)
	v_add_f32_e32 v0, v0, v67
	ds_swizzle_b32 v67, v0 offset:swizzle(SWAP,16)
	v_lshlrev_b32_e32 v222, 16, v117
	v_and_b32_e32 v223, 0xffff0000, v117
	v_lshlrev_b32_e32 v206, 16, v122
	v_and_b32_e32 v207, 0xffff0000, v122
	s_waitcnt lgkmcnt(0)
	v_add_f32_e32 v0, v0, v67
	v_lshlrev_b32_e32 v208, 16, v123
	v_readlane_b32 s1, v0, 32
	v_readlane_b32 s0, v0, 0
	v_and_b32_e32 v209, 0xffff0000, v123
	v_mov_b32_e32 v0, s1
	v_add_f32_e32 v0, s0, v0
	v_fmamk_f32 v0, v0, 0x39800000, v211
	v_mul_f32_e32 v67, 0x4f800000, v0
	v_cmp_gt_f32_e32 vcc, s94, v0
	v_lshlrev_b32_e32 v218, 16, v118
	v_and_b32_e32 v219, 0xffff0000, v118
	v_cndmask_b32_e32 v0, v0, v67, vcc
	v_sqrt_f32_e32 v67, v0
	v_lshlrev_b32_e32 v118, 16, v119
	v_and_b32_e32 v119, 0xffff0000, v119
	v_add_u32_e32 v102, -1, v67
	v_fma_f32 v103, -v102, v67, v0
	v_cmp_ge_f32_e64 s[0:1], 0, v103
	v_add_u32_e32 v103, 1, v67
	s_nop 0
	v_cndmask_b32_e64 v102, v67, v102, s[0:1]
	v_fma_f32 v67, -v103, v67, v0
	v_cmp_lt_f32_e64 s[0:1], 0, v67
	s_nop 1
	v_cndmask_b32_e64 v67, v102, v103, s[0:1]
	v_mul_f32_e32 v102, 0x37800000, v67
	v_cndmask_b32_e32 v67, v67, v102, vcc
	v_cmp_class_f32_e32 vcc, v0, v212
	s_nop 1
	v_cndmask_b32_e32 v0, v67, v0, vcc
	v_div_scale_f32 v67, s[0:1], v0, v0, 1.0
	v_rcp_f32_e32 v102, v67
	s_nop 0
	v_fma_f32 v98, -v67, v102, 1.0
	v_fmac_f32_e32 v102, v98, v102
	v_div_scale_f32 v98, vcc, 1.0, v0, 1.0
	v_mul_f32_e32 v99, v98, v102
	v_fma_f32 v103, -v67, v99, v98
	v_fmac_f32_e32 v99, v103, v102
	v_fma_f32 v67, -v67, v99, v98
	v_div_fmas_f32 v67, v67, v102, v99
	v_div_fixup_f32 v0, v67, v0, 1.0
	v_pk_mul_f32 v[98:99], v[0:1], v[194:195] op_sel_hi:[0,1]
	v_pk_fma_f32 v[98:99], v[4:5], v[98:99], v[112:113]
	v_pk_mul_f32 v[112:113], v[0:1], v[190:191] op_sel_hi:[0,1]
	v_pk_fma_f32 v[104:105], v[8:9], v[112:113], v[104:105]
	v_pk_mul_f32 v[112:113], v[0:1], v[186:187] op_sel_hi:[0,1]
	v_pk_mul_f32 v[102:103], v[0:1], v[196:197] op_sel_hi:[0,1]
	v_pk_fma_f32 v[106:107], v[12:13], v[112:113], v[106:107]
	v_pk_mul_f32 v[112:113], v[0:1], v[182:183] op_sel_hi:[0,1]
	v_pk_fma_f32 v[102:103], v[2:3], v[102:103], v[110:111]
	v_pk_mul_f32 v[110:111], v[0:1], v[192:193] op_sel_hi:[0,1]
	v_pk_fma_f32 v[96:97], v[16:17], v[112:113], v[96:97]
	v_pk_mul_f32 v[112:113], v[0:1], v[168:169] op_sel_hi:[0,1]
	v_pk_fma_f32 v[108:109], v[6:7], v[110:111], v[108:109]
	v_pk_mul_f32 v[110:111], v[0:1], v[188:189] op_sel_hi:[0,1]
	v_pk_fma_f32 v[92:93], v[20:21], v[112:113], v[92:93]
	v_pk_mul_f32 v[112:113], v[0:1], v[164:165] op_sel_hi:[0,1]
	v_pk_fma_f32 v[100:101], v[10:11], v[110:111], v[100:101]
	v_pk_mul_f32 v[110:111], v[0:1], v[184:185] op_sel_hi:[0,1]
	v_pk_fma_f32 v[88:89], v[24:25], v[112:113], v[88:89]
	v_pk_mul_f32 v[112:113], v[0:1], v[162:163] op_sel_hi:[0,1]
	v_pk_fma_f32 v[94:95], v[14:15], v[110:111], v[94:95]
	v_pk_mul_f32 v[110:111], v[0:1], v[180:181] op_sel_hi:[0,1]
	v_pk_fma_f32 v[114:115], v[26:27], v[112:113], v[82:83]
	v_pk_mul_f32 v[112:113], v[0:1], v[136:137] op_sel_hi:[0,1]
	v_cvt_pk_bf16_f32 v136, v102, v103
	v_cvt_pk_bf16_f32 v137, v98, v99
	v_pk_fma_f32 v[90:91], v[18:19], v[110:111], v[90:91]
	v_pk_mul_f32 v[110:111], v[0:1], v[166:167] op_sel_hi:[0,1]
	global_store_dwordx2 v[70:71], v[136:137], off
	v_cvt_pk_bf16_f32 v136, v108, v109
	v_cvt_pk_bf16_f32 v137, v104, v105
	v_pk_fma_f32 v[86:87], v[22:23], v[110:111], v[86:87]
	v_pk_mul_f32 v[110:111], v[0:1], v[160:161] op_sel_hi:[0,1]
	global_store_dwordx2 v[70:71], v[136:137], off offset:512
	v_cvt_pk_bf16_f32 v136, v100, v101
	v_cvt_pk_bf16_f32 v137, v106, v107
	v_pk_fma_f32 v[110:111], v[28:29], v[110:111], v[84:85]
	v_pk_mul_f32 v[82:83], v[0:1], v[158:159] op_sel_hi:[0,1]
	v_pk_mul_f32 v[84:85], v[0:1], v[156:157] op_sel_hi:[0,1]
	global_store_dwordx2 v[70:71], v[136:137], off offset:1024
	v_cvt_pk_bf16_f32 v136, v94, v95
	v_cvt_pk_bf16_f32 v137, v96, v97
	v_pk_fma_f32 v[116:117], v[32:33], v[84:85], v[80:81]
	v_pk_fma_f32 v[120:121], v[30:31], v[82:83], v[78:79]
	v_pk_mul_f32 v[78:79], v[0:1], v[154:155] op_sel_hi:[0,1]
	v_pk_mul_f32 v[80:81], v[0:1], v[126:127] op_sel_hi:[0,1]
	global_store_dwordx2 v[70:71], v[136:137], off offset:1536
	v_cvt_pk_bf16_f32 v136, v90, v91
	v_cvt_pk_bf16_f32 v137, v92, v93
	v_pk_fma_f32 v[122:123], v[44:45], v[80:81], v[76:77]
	v_pk_fma_f32 v[126:127], v[42:43], v[78:79], v[74:75]
	v_pk_mul_f32 v[76:77], v[0:1], v[152:153] op_sel_hi:[0,1]
	v_pk_mul_f32 v[78:79], v[0:1], v[144:145] op_sel_hi:[0,1]
	global_store_dwordx2 v[70:71], v[136:137], off offset:2048
	v_cvt_pk_bf16_f32 v136, v86, v87
	v_cvt_pk_bf16_f32 v137, v88, v89
	v_pk_mul_f32 v[74:75], v[0:1], v[130:131] op_sel_hi:[0,1]
	v_pk_fma_f32 v[130:131], v[34:35], v[76:77], v[72:73]
	v_pk_mul_f32 v[76:77], v[0:1], v[150:151] op_sel_hi:[0,1]
	v_pk_mul_f32 v[72:73], v[0:1], v[148:149] op_sel_hi:[0,1]
	v_pk_mul_f32 v[80:81], v[0:1], v[146:147] op_sel_hi:[0,1]
	v_pk_fma_f32 v[78:79], v[48:49], v[78:79], v[118:119]
	v_pk_mul_f32 v[84:85], v[0:1], v[142:143] op_sel_hi:[0,1]
	v_pk_mul_f32 v[82:83], v[0:1], v[140:141] op_sel_hi:[0,1]
	v_pk_mul_f32 v[118:119], v[0:1], v[138:139] op_sel_hi:[0,1]
	v_pk_mul_f32 v[128:129], v[0:1], v[128:129] op_sel_hi:[0,1]
	v_pk_mul_f32 v[124:125], v[0:1], v[124:125] op_sel_hi:[0,1]
	v_pk_mul_f32 v[134:135], v[0:1], v[134:135] op_sel_hi:[0,1]
	v_pk_mul_f32 v[132:133], v[0:1], v[132:133] op_sel_hi:[0,1]
	global_store_dwordx2 v[70:71], v[136:137], off offset:2560
	v_cvt_pk_bf16_f32 v136, v114, v115
	v_cvt_pk_bf16_f32 v137, v110, v111
	v_mul_f32_e32 v0, v103, v103
	v_mul_f32_e32 v67, v99, v99
	global_store_dwordx2 v[70:71], v[136:137], off offset:3072
	v_cvt_pk_bf16_f32 v136, v120, v121
	v_cvt_pk_bf16_f32 v137, v116, v117
	global_store_dwordx2 v[70:71], v[136:137], off offset:3584
	v_cvt_pk_bf16_f32 v70, v126, v127
	v_cvt_pk_bf16_f32 v71, v122, v123
	v_fmac_f32_e32 v0, v102, v102
	v_fmac_f32_e32 v67, v98, v98
	global_store_dwordx2 v[68:69], v[70:71], off
	v_add_f32_e32 v0, v0, v67
	v_mul_f32_e32 v67, v109, v109
	v_mul_f32_e32 v71, v105, v105
	v_fmac_f32_e32 v67, v108, v108
	v_fmac_f32_e32 v71, v104, v104
	v_add_f32_e32 v67, v67, v71
	v_add_f32_e32 v0, v0, v67
	v_mul_f32_e32 v67, v101, v101
	v_mul_f32_e32 v71, v107, v107
	v_fmac_f32_e32 v67, v100, v100
	v_fmac_f32_e32 v71, v106, v106
	v_add_f32_e32 v67, v67, v71
	v_add_f32_e32 v0, v67, v0
	v_mul_f32_e32 v67, v95, v95
	v_mul_f32_e32 v71, v97, v97
	v_fmac_f32_e32 v67, v94, v94
	v_fmac_f32_e32 v71, v96, v96
	v_add_f32_e32 v67, v67, v71
	v_add_f32_e32 v0, v67, v0
	v_mul_f32_e32 v67, v91, v91
	v_mul_f32_e32 v71, v93, v93
	v_fmac_f32_e32 v67, v90, v90
	v_fmac_f32_e32 v71, v92, v92
	v_add_f32_e32 v67, v67, v71
	v_add_f32_e32 v0, v67, v0
	v_mul_f32_e32 v67, v87, v87
	v_mul_f32_e32 v71, v89, v89
	v_fmac_f32_e32 v67, v86, v86
	v_fmac_f32_e32 v71, v88, v88
	v_add_f32_e32 v67, v67, v71
	v_add_f32_e32 v0, v67, v0
	v_mul_f32_e32 v67, v115, v115
	v_mul_f32_e32 v71, v111, v111
	v_fmac_f32_e32 v67, v114, v114
	v_fmac_f32_e32 v71, v110, v110
	v_add_f32_e32 v67, v67, v71
	v_add_f32_e32 v0, v67, v0
	v_mul_f32_e32 v67, v121, v121
	v_mul_f32_e32 v71, v117, v117
	v_fmac_f32_e32 v67, v120, v120
	v_fmac_f32_e32 v71, v116, v116
	v_add_f32_e32 v67, v67, v71
	v_add_f32_e32 v0, v67, v0
	v_mul_f32_e32 v67, v127, v127
	v_mul_f32_e32 v71, v123, v123
	v_fmac_f32_e32 v67, v126, v126
	v_fmac_f32_e32 v71, v122, v122
	v_pk_fma_f32 v[74:75], v[36:37], v[74:75], v[204:205]
	v_add_f32_e32 v67, v67, v71
	v_add_f32_e32 v0, v67, v0
	v_mul_f32_e32 v67, v131, v131
	v_mul_f32_e32 v71, v75, v75
	v_fmac_f32_e32 v67, v130, v130
	v_fmac_f32_e32 v71, v74, v74
	v_pk_fma_f32 v[72:73], v[40:41], v[72:73], v[208:209]
	v_pk_fma_f32 v[76:77], v[38:39], v[76:77], v[206:207]
	v_add_f32_e32 v67, v67, v71
	v_add_f32_e32 v0, v67, v0
	v_mul_f32_e32 v67, v77, v77
	v_mul_f32_e32 v71, v73, v73
	v_fmac_f32_e32 v67, v76, v76
	v_fmac_f32_e32 v71, v72, v72
	v_pk_fma_f32 v[80:81], v[46:47], v[80:81], v[218:219]
	v_add_f32_e32 v67, v67, v71
	v_add_f32_e32 v0, v67, v0
	v_mul_f32_e32 v67, v81, v81
	v_mul_f32_e32 v71, v79, v79
	v_fmac_f32_e32 v67, v80, v80
	v_fmac_f32_e32 v71, v78, v78
	v_pk_fma_f32 v[82:83], v[52:53], v[82:83], v[222:223]
	v_pk_fma_f32 v[84:85], v[50:51], v[84:85], v[220:221]
	v_add_f32_e32 v67, v67, v71
	v_add_f32_e32 v0, v67, v0
	v_mul_f32_e32 v67, v85, v85
	v_mul_f32_e32 v71, v83, v83
	v_fmac_f32_e32 v67, v84, v84
	v_fmac_f32_e32 v71, v82, v82
	v_pk_fma_f32 v[112:113], v[56:57], v[112:113], v[226:227]
	v_pk_fma_f32 v[118:119], v[54:55], v[118:119], v[224:225]
	v_add_f32_e32 v67, v67, v71
	v_add_f32_e32 v0, v67, v0
	v_mul_f32_e32 v67, v119, v119
	v_mul_f32_e32 v71, v113, v113
	v_fmac_f32_e32 v67, v118, v118
	v_fmac_f32_e32 v71, v112, v112
	v_pk_fma_f32 v[124:125], v[60:61], v[124:125], v[228:229]
	v_pk_fma_f32 v[128:129], v[58:59], v[128:129], v[198:199]
	v_add_f32_e32 v67, v67, v71
	v_add_f32_e32 v0, v67, v0
	v_mul_f32_e32 v67, v129, v129
	v_mul_f32_e32 v71, v125, v125
	v_fmac_f32_e32 v67, v128, v128
	v_fmac_f32_e32 v71, v124, v124
	v_pk_fma_f32 v[132:133], v[64:65], v[132:133], v[230:231]
	v_pk_fma_f32 v[134:135], v[62:63], v[134:135], v[200:201]
	v_add_f32_e32 v67, v67, v71
	v_add_f32_e32 v0, v67, v0
	v_mul_f32_e32 v67, v135, v135
	v_mul_f32_e32 v71, v133, v133
	v_fmac_f32_e32 v67, v134, v134
	v_fmac_f32_e32 v71, v132, v132
	v_add_f32_e32 v67, v67, v71
	v_add_f32_e32 v0, v67, v0
	ds_swizzle_b32 v67, v0 offset:swizzle(SWAP,1)
	v_cvt_pk_bf16_f32 v70, v130, v131
	v_cvt_pk_bf16_f32 v71, v74, v75
	global_store_dwordx2 v[68:69], v[70:71], off offset:512
	v_cvt_pk_bf16_f32 v70, v76, v77
	s_waitcnt lgkmcnt(0)
	v_add_f32_e32 v0, v0, v67
	ds_swizzle_b32 v67, v0 offset:swizzle(SWAP,2)
	v_cvt_pk_bf16_f32 v71, v72, v73
	global_store_dwordx2 v[68:69], v[70:71], off offset:1024
	v_cvt_pk_bf16_f32 v70, v80, v81
	v_cvt_pk_bf16_f32 v71, v78, v79
	s_waitcnt lgkmcnt(0)
	v_add_f32_e32 v0, v0, v67
	ds_swizzle_b32 v67, v0 offset:swizzle(SWAP,4)
	global_store_dwordx2 v[68:69], v[70:71], off offset:1536
	v_cvt_pk_bf16_f32 v70, v84, v85
	v_cvt_pk_bf16_f32 v71, v82, v83
	global_store_dwordx2 v[68:69], v[70:71], off offset:2048
	s_waitcnt lgkmcnt(0)
	v_add_f32_e32 v0, v0, v67
	ds_swizzle_b32 v67, v0 offset:swizzle(SWAP,8)
	v_cvt_pk_bf16_f32 v70, v118, v119
	v_cvt_pk_bf16_f32 v71, v112, v113
	global_store_dwordx2 v[68:69], v[70:71], off offset:2560
	v_cvt_pk_bf16_f32 v70, v128, v129
	s_waitcnt lgkmcnt(0)
	v_add_f32_e32 v0, v0, v67
	ds_swizzle_b32 v67, v0 offset:swizzle(SWAP,16)
	v_cvt_pk_bf16_f32 v71, v124, v125
	v_cmp_eq_u32_e32 vcc, 0, v66
	global_store_dwordx2 v[68:69], v[70:71], off offset:3072
	v_cvt_pk_bf16_f32 v70, v134, v135
	s_waitcnt lgkmcnt(0)
	v_add_f32_e32 v0, v0, v67
	v_cvt_pk_bf16_f32 v71, v132, v133
	global_store_dwordx2 v[68:69], v[70:71], off offset:3584
	v_readlane_b32 s0, v0, 0
	v_readlane_b32 s1, v0, 32
	s_and_saveexec_b64 s[4:5], vcc
	s_cbranch_execz .LBB0_804
	v_mov_b32_e32 v0, s1
	v_add_f32_e32 v0, s0, v0
	v_fmamk_f32 v0, v0, 0x39800000, v211
	v_mul_f32_e32 v66, 0x4f800000, v0
	v_cmp_gt_f32_e32 vcc, s94, v0
	v_readlane_b32 s16, v252, 0
	v_readlane_b32 s18, v252, 2
	v_cndmask_b32_e32 v0, v0, v66, vcc
	v_sqrt_f32_e32 v66, v0
	v_readlane_b32 s19, v252, 3
	v_readlane_b32 s17, v252, 1
	v_add_u32_e32 v67, -1, v66
	v_fma_f32 v69, -v67, v66, v0
	v_add_u32_e32 v68, 1, v66
	v_cmp_ge_f32_e64 s[0:1], 0, v69
	s_nop 1
	v_cndmask_b32_e64 v67, v66, v67, s[0:1]
	v_fma_f32 v66, -v68, v66, v0
	v_cmp_lt_f32_e64 s[0:1], 0, v66
	s_nop 1
	v_cndmask_b32_e64 v66, v67, v68, s[0:1]
	v_mul_f32_e32 v67, 0x37800000, v66
	v_cndmask_b32_e32 v66, v66, v67, vcc
	v_cmp_class_f32_e32 vcc, v0, v212
	s_nop 1
	v_cndmask_b32_e32 v0, v66, v0, vcc
	v_div_scale_f32 v66, s[0:1], v0, v0, 1.0
	v_rcp_f32_e32 v67, v66
	s_add_u32 s0, s18, s7
	s_addc_u32 s1, s19, s8
	v_fma_f32 v68, -v66, v67, 1.0
	v_fmac_f32_e32 v67, v68, v67
	v_div_scale_f32 v68, vcc, 1.0, v0, 1.0
	v_mul_f32_e32 v69, v68, v67
	v_fma_f32 v70, -v66, v69, v68
	v_fmac_f32_e32 v69, v70, v67
	v_fma_f32 v66, -v66, v69, v68
	v_div_fmas_f32 v66, v66, v67, v69
	v_div_fixup_f32 v0, v66, v0, 1.0
	global_store_dword v1, v0, s[0:1]
	s_branch .LBB0_804

.LBB0_1241:
	v_readlane_b32 s16, v252, 0
	v_readlane_b32 s18, v252, 2
	v_mov_b32_e32 v68, v204
	v_readlane_b32 s19, v252, 3
	s_add_u32 s0, s18, s2
	s_addc_u32 s1, s19, s3
	v_ashrrev_i32_e32 v69, 31, v68
	v_lshl_add_u64 v[74:75], v[68:69], 3, s[0:1]
	v_add_co_u32_e32 v72, vcc, 0x44700000, v74
	v_readlane_b32 s17, v252, 1
	s_nop 0
	v_addc_co_u32_e32 v73, vcc, 0, v75, vcc
	v_add_co_u32_e32 v70, vcc, 0x44701000, v74
	global_load_dwordx2 v[76:77], v[72:73], off
	global_load_dwordx2 v[78:79], v[72:73], off offset:512
	global_load_dwordx2 v[80:81], v[72:73], off offset:1024
	global_load_dwordx2 v[82:83], v[72:73], off offset:1536
	global_load_dwordx2 v[84:85], v[72:73], off offset:2048
	global_load_dwordx2 v[86:87], v[72:73], off offset:2560
	global_load_dwordx2 v[126:127], v[72:73], off offset:3072
	v_addc_co_u32_e32 v71, vcc, 0, v75, vcc
	global_load_dwordx2 v[128:129], v[72:73], off offset:3584
	global_load_dwordx2 v[130:131], v[70:71], off
	global_load_dwordx2 v[122:123], v[70:71], off offset:512
	v_add_co_u32_e32 v88, vcc, 0x3a200000, v74
	s_nop 1
	v_addc_co_u32_e32 v89, vcc, 0, v75, vcc
	global_load_dwordx2 v[132:133], v[88:89], off
	global_load_dwordx2 v[134:135], v[88:89], off offset:512
	global_load_dwordx2 v[124:125], v[70:71], off offset:1024
	global_load_dwordx2 v[120:121], v[70:71], off offset:1536
	global_load_dwordx2 v[136:137], v[88:89], off offset:1024
	global_load_dwordx2 v[118:119], v[70:71], off offset:2048
	global_load_dwordx2 v[116:117], v[70:71], off offset:2560
	global_load_dwordx2 v[104:105], v[70:71], off offset:3072
	global_load_dwordx2 v[100:101], v[70:71], off offset:3584
	global_load_dwordx2 v[138:139], v[88:89], off offset:1536
	global_load_dwordx2 v[140:141], v[88:89], off offset:2048
	global_load_dwordx2 v[142:143], v[88:89], off offset:2560
	global_load_dwordx2 v[144:145], v[88:89], off offset:3072
	global_load_dwordx2 v[146:147], v[88:89], off offset:3584
	v_add_co_u32_e32 v74, vcc, 0x3a201000, v74
	s_nop 1
	v_addc_co_u32_e32 v75, vcc, 0, v75, vcc
	global_load_dwordx2 v[148:149], v[74:75], off
	global_load_dwordx2 v[150:151], v[74:75], off offset:512
	global_load_dwordx2 v[200:201], v[74:75], off offset:1024
	global_load_dwordx2 v[202:203], v[74:75], off offset:1536
	global_load_dwordx2 v[206:207], v[74:75], off offset:2048
	global_load_dwordx2 v[208:209], v[74:75], off offset:2560
	global_load_dwordx2 v[218:219], v[74:75], off offset:3072
	global_load_dwordx2 v[220:221], v[74:75], off offset:3584
	s_waitcnt vmcnt(22)
	v_lshlrev_b32_e32 v112, 16, v76
	v_lshlrev_b32_e32 v96, 16, v82
	v_lshlrev_b32_e32 v74, 16, v122
	v_and_b32_e32 v75, 0xffff0000, v122
	v_and_b32_e32 v97, 0xffff0000, v82
	v_lshlrev_b32_e32 v98, 16, v83
	v_and_b32_e32 v99, 0xffff0000, v83
	v_lshlrev_b32_e32 v82, 16, v129
	v_and_b32_e32 v83, 0xffff0000, v129
	v_lshlrev_b32_e32 v102, 16, v80
	v_and_b32_e32 v103, 0xffff0000, v80
	v_lshlrev_b32_e32 v108, 16, v81
	v_and_b32_e32 v109, 0xffff0000, v81
	v_lshlrev_b32_e32 v80, 16, v128
	v_and_b32_e32 v81, 0xffff0000, v128
	v_lshlrev_b32_e32 v110, 16, v78
	v_and_b32_e32 v111, 0xffff0000, v78
	v_lshlrev_b32_e32 v106, 16, v79
	v_and_b32_e32 v107, 0xffff0000, v79
	v_lshlrev_b32_e32 v88, 16, v86
	v_and_b32_e32 v89, 0xffff0000, v86
	v_lshlrev_b32_e32 v90, 16, v87
	v_and_b32_e32 v91, 0xffff0000, v87
	v_lshlrev_b32_e32 v86, 16, v127
	v_and_b32_e32 v87, 0xffff0000, v127
	v_lshlrev_b32_e32 v78, 16, v131
	v_and_b32_e32 v79, 0xffff0000, v131
	v_and_b32_e32 v113, 0xffff0000, v76
	v_lshlrev_b32_e32 v114, 16, v77
	v_and_b32_e32 v115, 0xffff0000, v77
	v_lshlrev_b32_e32 v92, 16, v84
	v_and_b32_e32 v93, 0xffff0000, v84
	v_lshlrev_b32_e32 v94, 16, v85
	v_and_b32_e32 v95, 0xffff0000, v85
	v_lshlrev_b32_e32 v84, 16, v126
	v_and_b32_e32 v85, 0xffff0000, v126
	v_lshlrev_b32_e32 v76, 16, v130
	v_and_b32_e32 v77, 0xffff0000, v130
	s_waitcnt vmcnt(21)
	v_and_b32_e32 v199, 0xffff0000, v132
	v_and_b32_e32 v197, 0xffff0000, v133
	v_lshlrev_b32_e32 v198, 16, v132
	v_lshlrev_b32_e32 v196, 16, v133
	v_mul_f32_e32 v0, v199, v199
	v_mul_f32_e32 v69, v197, v197
	v_fmac_f32_e32 v0, v198, v198
	v_fmac_f32_e32 v69, v196, v196
	s_waitcnt vmcnt(20)
	v_and_b32_e32 v195, 0xffff0000, v134
	v_and_b32_e32 v193, 0xffff0000, v135
	v_add_f32_e32 v0, v0, v69
	v_lshlrev_b32_e32 v194, 16, v134
	v_lshlrev_b32_e32 v192, 16, v135
	v_mul_f32_e32 v69, v195, v195
	v_mul_f32_e32 v122, v193, v193
	v_fmac_f32_e32 v69, v194, v194
	v_fmac_f32_e32 v122, v192, v192
	v_add_f32_e32 v69, v69, v122
	s_waitcnt vmcnt(17)
	v_and_b32_e32 v191, 0xffff0000, v136
	v_and_b32_e32 v189, 0xffff0000, v137
	v_add_f32_e32 v0, v0, v69
	v_lshlrev_b32_e32 v190, 16, v136
	v_lshlrev_b32_e32 v188, 16, v137
	v_mul_f32_e32 v69, v191, v191
	v_mul_f32_e32 v122, v189, v189
	v_fmac_f32_e32 v69, v190, v190
	v_fmac_f32_e32 v122, v188, v188
	v_add_f32_e32 v69, v69, v122
	s_waitcnt vmcnt(12)
	v_and_b32_e32 v187, 0xffff0000, v138
	v_and_b32_e32 v185, 0xffff0000, v139
	v_add_f32_e32 v0, v0, v69
	v_lshlrev_b32_e32 v186, 16, v138
	v_lshlrev_b32_e32 v184, 16, v139
	v_mul_f32_e32 v69, v187, v187
	v_mul_f32_e32 v122, v185, v185
	v_fmac_f32_e32 v69, v186, v186
	v_fmac_f32_e32 v122, v184, v184
	v_add_f32_e32 v69, v69, v122
	s_waitcnt vmcnt(11)
	v_and_b32_e32 v183, 0xffff0000, v140
	v_and_b32_e32 v181, 0xffff0000, v141
	v_add_f32_e32 v0, v0, v69
	v_lshlrev_b32_e32 v182, 16, v140
	v_lshlrev_b32_e32 v180, 16, v141
	v_mul_f32_e32 v69, v183, v183
	v_mul_f32_e32 v122, v181, v181
	v_fmac_f32_e32 v69, v182, v182
	v_fmac_f32_e32 v122, v180, v180
	v_add_f32_e32 v69, v69, v122
	s_waitcnt vmcnt(10)
	v_and_b32_e32 v169, 0xffff0000, v142
	v_and_b32_e32 v167, 0xffff0000, v143
	v_add_f32_e32 v0, v0, v69
	v_lshlrev_b32_e32 v168, 16, v142
	v_lshlrev_b32_e32 v166, 16, v143
	v_mul_f32_e32 v69, v169, v169
	v_mul_f32_e32 v122, v167, v167
	v_fmac_f32_e32 v69, v168, v168
	v_fmac_f32_e32 v122, v166, v166
	v_add_f32_e32 v69, v69, v122
	s_waitcnt vmcnt(9)
	v_and_b32_e32 v165, 0xffff0000, v144
	v_and_b32_e32 v163, 0xffff0000, v145
	v_add_f32_e32 v0, v0, v69
	v_lshlrev_b32_e32 v164, 16, v144
	v_lshlrev_b32_e32 v162, 16, v145
	v_mul_f32_e32 v69, v165, v165
	v_mul_f32_e32 v122, v163, v163
	v_fmac_f32_e32 v69, v164, v164
	v_fmac_f32_e32 v122, v162, v162
	v_add_f32_e32 v69, v69, v122
	s_waitcnt vmcnt(8)
	v_and_b32_e32 v161, 0xffff0000, v146
	v_and_b32_e32 v159, 0xffff0000, v147
	v_add_f32_e32 v0, v0, v69
	v_lshlrev_b32_e32 v160, 16, v146
	v_lshlrev_b32_e32 v158, 16, v147
	v_mul_f32_e32 v69, v161, v161
	v_mul_f32_e32 v122, v159, v159
	v_fmac_f32_e32 v69, v160, v160
	v_fmac_f32_e32 v122, v158, v158
	v_add_f32_e32 v69, v69, v122
	s_waitcnt vmcnt(7)
	v_and_b32_e32 v157, 0xffff0000, v148
	v_and_b32_e32 v129, 0xffff0000, v149
	v_add_f32_e32 v0, v0, v69
	v_lshlrev_b32_e32 v156, 16, v148
	v_lshlrev_b32_e32 v128, 16, v149
	v_mul_f32_e32 v69, v157, v157
	v_mul_f32_e32 v122, v129, v129
	v_fmac_f32_e32 v69, v156, v156
	v_fmac_f32_e32 v122, v128, v128
	v_add_f32_e32 v69, v69, v122
	s_waitcnt vmcnt(6)
	v_and_b32_e32 v155, 0xffff0000, v150
	v_and_b32_e32 v133, 0xffff0000, v151
	v_add_f32_e32 v0, v0, v69
	v_lshlrev_b32_e32 v154, 16, v150
	v_lshlrev_b32_e32 v132, 16, v151
	v_mul_f32_e32 v69, v155, v155
	v_mul_f32_e32 v122, v133, v133
	v_fmac_f32_e32 v69, v154, v154
	v_fmac_f32_e32 v122, v132, v132
	v_add_f32_e32 v69, v69, v122
	s_waitcnt vmcnt(5)
	v_and_b32_e32 v153, 0xffff0000, v200
	v_and_b32_e32 v151, 0xffff0000, v201
	v_add_f32_e32 v0, v0, v69
	v_lshlrev_b32_e32 v152, 16, v200
	v_lshlrev_b32_e32 v150, 16, v201
	v_mul_f32_e32 v69, v153, v153
	v_mul_f32_e32 v122, v151, v151
	v_fmac_f32_e32 v69, v152, v152
	v_fmac_f32_e32 v122, v150, v150
	v_add_f32_e32 v69, v69, v122
	s_waitcnt vmcnt(4)
	v_and_b32_e32 v149, 0xffff0000, v202
	v_and_b32_e32 v147, 0xffff0000, v203
	v_add_f32_e32 v0, v0, v69
	v_lshlrev_b32_e32 v148, 16, v202
	v_lshlrev_b32_e32 v146, 16, v203
	v_mul_f32_e32 v69, v149, v149
	v_mul_f32_e32 v122, v147, v147
	v_fmac_f32_e32 v69, v148, v148
	v_fmac_f32_e32 v122, v146, v146
	v_add_f32_e32 v69, v69, v122
	s_waitcnt vmcnt(3)
	v_and_b32_e32 v145, 0xffff0000, v206
	v_and_b32_e32 v143, 0xffff0000, v207
	v_add_f32_e32 v0, v0, v69
	v_lshlrev_b32_e32 v144, 16, v206
	v_lshlrev_b32_e32 v142, 16, v207
	v_mul_f32_e32 v69, v145, v145
	v_mul_f32_e32 v122, v143, v143
	v_fmac_f32_e32 v69, v144, v144
	v_fmac_f32_e32 v122, v142, v142
	v_add_f32_e32 v69, v69, v122
	s_waitcnt vmcnt(2)
	v_and_b32_e32 v141, 0xffff0000, v208
	v_and_b32_e32 v139, 0xffff0000, v209
	v_add_f32_e32 v0, v0, v69
	v_lshlrev_b32_e32 v140, 16, v208
	v_lshlrev_b32_e32 v138, 16, v209
	v_mul_f32_e32 v69, v141, v141
	v_mul_f32_e32 v122, v139, v139
	v_fmac_f32_e32 v69, v140, v140
	v_fmac_f32_e32 v122, v138, v138
	v_add_f32_e32 v69, v69, v122
	s_waitcnt vmcnt(1)
	v_and_b32_e32 v131, 0xffff0000, v218
	v_and_b32_e32 v127, 0xffff0000, v219
	v_add_f32_e32 v0, v0, v69
	v_lshlrev_b32_e32 v130, 16, v218
	v_lshlrev_b32_e32 v126, 16, v219
	v_mul_f32_e32 v69, v131, v131
	v_mul_f32_e32 v122, v127, v127
	v_fmac_f32_e32 v69, v130, v130
	v_fmac_f32_e32 v122, v126, v126
	v_add_f32_e32 v69, v69, v122
	s_waitcnt vmcnt(0)
	v_and_b32_e32 v137, 0xffff0000, v220
	v_and_b32_e32 v135, 0xffff0000, v221
	v_add_f32_e32 v0, v0, v69
	v_lshlrev_b32_e32 v136, 16, v220
	v_lshlrev_b32_e32 v134, 16, v221
	v_mul_f32_e32 v69, v137, v137
	v_mul_f32_e32 v122, v135, v135
	v_fmac_f32_e32 v69, v136, v136
	v_fmac_f32_e32 v122, v134, v134
	v_add_f32_e32 v69, v69, v122
	v_add_f32_e32 v0, v0, v69
	ds_swizzle_b32 v69, v0 offset:swizzle(SWAP,1)
	v_lshlrev_b32_e32 v200, 16, v104
	v_and_b32_e32 v201, 0xffff0000, v104
	v_lshlrev_b32_e32 v230, 16, v105
	v_and_b32_e32 v231, 0xffff0000, v105
	s_waitcnt lgkmcnt(0)
	v_add_f32_e32 v0, v0, v69
	ds_swizzle_b32 v69, v0 offset:swizzle(SWAP,2)
	v_lshlrev_b32_e32 v202, 16, v100
	v_and_b32_e32 v203, 0xffff0000, v100
	v_lshlrev_b32_e32 v232, 16, v101
	v_and_b32_e32 v233, 0xffff0000, v101
	s_waitcnt lgkmcnt(0)
	v_add_f32_e32 v0, v0, v69
	ds_swizzle_b32 v69, v0 offset:swizzle(SWAP,4)
	v_lshlrev_b32_e32 v226, 16, v116
	v_and_b32_e32 v227, 0xffff0000, v116
	v_lshlrev_b32_e32 v228, 16, v117
	v_and_b32_e32 v229, 0xffff0000, v117
	s_waitcnt lgkmcnt(0)
	v_add_f32_e32 v0, v0, v69
	ds_swizzle_b32 v69, v0 offset:swizzle(SWAP,8)
	v_lshlrev_b32_e32 v206, 16, v123
	v_and_b32_e32 v207, 0xffff0000, v123
	v_lshlrev_b32_e32 v222, 16, v118
	v_and_b32_e32 v223, 0xffff0000, v118
	s_waitcnt lgkmcnt(0)
	v_add_f32_e32 v0, v0, v69
	ds_swizzle_b32 v69, v0 offset:swizzle(SWAP,16)
	v_lshlrev_b32_e32 v224, 16, v119
	v_and_b32_e32 v225, 0xffff0000, v119
	v_lshlrev_b32_e32 v208, 16, v124
	v_and_b32_e32 v209, 0xffff0000, v124
	s_waitcnt lgkmcnt(0)
	v_add_f32_e32 v0, v0, v69
	v_lshlrev_b32_e32 v218, 16, v125
	v_readlane_b32 s1, v0, 32
	v_readlane_b32 s0, v0, 0
	v_and_b32_e32 v219, 0xffff0000, v125
	v_mov_b32_e32 v0, s1
	v_add_f32_e32 v0, s0, v0
	v_fmamk_f32 v0, v0, 0x39800000, v211
	v_mul_f32_e32 v69, 0x4f800000, v0
	v_cmp_gt_f32_e32 vcc, s94, v0
	v_lshlrev_b32_e32 v220, 16, v120
	v_and_b32_e32 v221, 0xffff0000, v120
	v_cndmask_b32_e32 v0, v0, v69, vcc
	v_sqrt_f32_e32 v69, v0
	v_lshlrev_b32_e32 v120, 16, v121
	v_and_b32_e32 v121, 0xffff0000, v121
	v_add_u32_e32 v104, -1, v69
	v_fma_f32 v105, -v104, v69, v0
	v_cmp_ge_f32_e64 s[0:1], 0, v105
	v_add_u32_e32 v105, 1, v69
	s_nop 0
	v_cndmask_b32_e64 v104, v69, v104, s[0:1]
	v_fma_f32 v69, -v105, v69, v0
	v_cmp_lt_f32_e64 s[0:1], 0, v69
	s_nop 1
	v_cndmask_b32_e64 v69, v104, v105, s[0:1]
	v_mul_f32_e32 v104, 0x37800000, v69
	v_cndmask_b32_e32 v69, v69, v104, vcc
	v_cmp_class_f32_e32 vcc, v0, v212
	s_nop 1
	v_cndmask_b32_e32 v0, v69, v0, vcc
	v_div_scale_f32 v69, s[0:1], v0, v0, 1.0
	v_rcp_f32_e32 v104, v69
	s_nop 0
	v_fma_f32 v100, -v69, v104, 1.0
	v_fmac_f32_e32 v104, v100, v104
	v_div_scale_f32 v100, vcc, 1.0, v0, 1.0
	v_mul_f32_e32 v101, v100, v104
	v_fma_f32 v105, -v69, v101, v100
	v_fmac_f32_e32 v101, v105, v104
	v_fma_f32 v69, -v69, v101, v100
	v_div_fmas_f32 v69, v69, v104, v101
	v_div_fixup_f32 v0, v69, v0, 1.0
	v_pk_mul_f32 v[100:101], v[0:1], v[196:197] op_sel_hi:[0,1]
	v_pk_fma_f32 v[100:101], v[4:5], v[100:101], v[114:115]
	v_pk_mul_f32 v[114:115], v[0:1], v[192:193] op_sel_hi:[0,1]
	v_pk_fma_f32 v[106:107], v[8:9], v[114:115], v[106:107]
	v_pk_mul_f32 v[114:115], v[0:1], v[188:189] op_sel_hi:[0,1]
	v_pk_mul_f32 v[104:105], v[0:1], v[198:199] op_sel_hi:[0,1]
	v_pk_fma_f32 v[108:109], v[12:13], v[114:115], v[108:109]
	v_pk_mul_f32 v[114:115], v[0:1], v[184:185] op_sel_hi:[0,1]
	v_pk_fma_f32 v[104:105], v[2:3], v[104:105], v[112:113]
	v_pk_mul_f32 v[112:113], v[0:1], v[194:195] op_sel_hi:[0,1]
	v_pk_fma_f32 v[98:99], v[16:17], v[114:115], v[98:99]
	v_pk_mul_f32 v[114:115], v[0:1], v[180:181] op_sel_hi:[0,1]
	v_pk_fma_f32 v[110:111], v[6:7], v[112:113], v[110:111]
	v_pk_mul_f32 v[112:113], v[0:1], v[190:191] op_sel_hi:[0,1]
	v_pk_fma_f32 v[94:95], v[20:21], v[114:115], v[94:95]
	v_pk_mul_f32 v[114:115], v[0:1], v[166:167] op_sel_hi:[0,1]
	v_pk_fma_f32 v[102:103], v[10:11], v[112:113], v[102:103]
	v_pk_mul_f32 v[112:113], v[0:1], v[186:187] op_sel_hi:[0,1]
	v_pk_fma_f32 v[90:91], v[24:25], v[114:115], v[90:91]
	v_pk_mul_f32 v[114:115], v[0:1], v[164:165] op_sel_hi:[0,1]
	v_pk_fma_f32 v[96:97], v[14:15], v[112:113], v[96:97]
	v_pk_mul_f32 v[112:113], v[0:1], v[182:183] op_sel_hi:[0,1]
	v_pk_fma_f32 v[116:117], v[26:27], v[114:115], v[84:85]
	v_pk_mul_f32 v[114:115], v[0:1], v[138:139] op_sel_hi:[0,1]
	v_cvt_pk_bf16_f32 v138, v104, v105
	v_cvt_pk_bf16_f32 v139, v100, v101
	v_pk_fma_f32 v[92:93], v[18:19], v[112:113], v[92:93]
	v_pk_mul_f32 v[112:113], v[0:1], v[168:169] op_sel_hi:[0,1]
	global_store_dwordx2 v[72:73], v[138:139], off
	v_cvt_pk_bf16_f32 v138, v110, v111
	v_cvt_pk_bf16_f32 v139, v106, v107
	v_pk_fma_f32 v[88:89], v[22:23], v[112:113], v[88:89]
	v_pk_mul_f32 v[112:113], v[0:1], v[162:163] op_sel_hi:[0,1]
	global_store_dwordx2 v[72:73], v[138:139], off offset:512
	v_cvt_pk_bf16_f32 v138, v102, v103
	v_cvt_pk_bf16_f32 v139, v108, v109
	v_pk_fma_f32 v[112:113], v[28:29], v[112:113], v[86:87]
	v_pk_mul_f32 v[84:85], v[0:1], v[160:161] op_sel_hi:[0,1]
	v_pk_mul_f32 v[86:87], v[0:1], v[158:159] op_sel_hi:[0,1]
	global_store_dwordx2 v[72:73], v[138:139], off offset:1024
	v_cvt_pk_bf16_f32 v138, v96, v97
	v_cvt_pk_bf16_f32 v139, v98, v99
	v_pk_fma_f32 v[118:119], v[32:33], v[86:87], v[82:83]
	v_pk_fma_f32 v[122:123], v[30:31], v[84:85], v[80:81]
	v_pk_mul_f32 v[80:81], v[0:1], v[156:157] op_sel_hi:[0,1]
	v_pk_mul_f32 v[82:83], v[0:1], v[128:129] op_sel_hi:[0,1]
	global_store_dwordx2 v[72:73], v[138:139], off offset:1536
	v_cvt_pk_bf16_f32 v138, v92, v93
	v_cvt_pk_bf16_f32 v139, v94, v95
	v_pk_fma_f32 v[124:125], v[44:45], v[82:83], v[78:79]
	v_pk_fma_f32 v[128:129], v[42:43], v[80:81], v[76:77]
	v_pk_mul_f32 v[78:79], v[0:1], v[154:155] op_sel_hi:[0,1]
	v_pk_mul_f32 v[80:81], v[0:1], v[146:147] op_sel_hi:[0,1]
	global_store_dwordx2 v[72:73], v[138:139], off offset:2048
	v_cvt_pk_bf16_f32 v138, v88, v89
	v_cvt_pk_bf16_f32 v139, v90, v91
	v_pk_mul_f32 v[76:77], v[0:1], v[132:133] op_sel_hi:[0,1]
	v_pk_fma_f32 v[132:133], v[34:35], v[78:79], v[74:75]
	v_pk_mul_f32 v[78:79], v[0:1], v[152:153] op_sel_hi:[0,1]
	v_pk_mul_f32 v[74:75], v[0:1], v[150:151] op_sel_hi:[0,1]
	v_pk_mul_f32 v[82:83], v[0:1], v[148:149] op_sel_hi:[0,1]
	v_pk_fma_f32 v[80:81], v[48:49], v[80:81], v[120:121]
	v_pk_mul_f32 v[86:87], v[0:1], v[144:145] op_sel_hi:[0,1]
	v_pk_mul_f32 v[84:85], v[0:1], v[142:143] op_sel_hi:[0,1]
	v_pk_mul_f32 v[120:121], v[0:1], v[140:141] op_sel_hi:[0,1]
	v_pk_mul_f32 v[130:131], v[0:1], v[130:131] op_sel_hi:[0,1]
	v_pk_mul_f32 v[126:127], v[0:1], v[126:127] op_sel_hi:[0,1]
	v_pk_mul_f32 v[136:137], v[0:1], v[136:137] op_sel_hi:[0,1]
	v_pk_mul_f32 v[134:135], v[0:1], v[134:135] op_sel_hi:[0,1]
	global_store_dwordx2 v[72:73], v[138:139], off offset:2560
	v_cvt_pk_bf16_f32 v138, v116, v117
	v_cvt_pk_bf16_f32 v139, v112, v113
	v_mul_f32_e32 v0, v105, v105
	v_mul_f32_e32 v69, v101, v101
	global_store_dwordx2 v[72:73], v[138:139], off offset:3072
	v_cvt_pk_bf16_f32 v138, v122, v123
	v_cvt_pk_bf16_f32 v139, v118, v119
	global_store_dwordx2 v[72:73], v[138:139], off offset:3584
	v_cvt_pk_bf16_f32 v72, v128, v129
	v_cvt_pk_bf16_f32 v73, v124, v125
	v_fmac_f32_e32 v0, v104, v104
	v_fmac_f32_e32 v69, v100, v100
	global_store_dwordx2 v[70:71], v[72:73], off
	v_add_f32_e32 v0, v0, v69
	v_mul_f32_e32 v69, v111, v111
	v_mul_f32_e32 v73, v107, v107
	v_fmac_f32_e32 v69, v110, v110
	v_fmac_f32_e32 v73, v106, v106
	v_add_f32_e32 v69, v69, v73
	v_add_f32_e32 v0, v0, v69
	v_mul_f32_e32 v69, v103, v103
	v_mul_f32_e32 v73, v109, v109
	v_fmac_f32_e32 v69, v102, v102
	v_fmac_f32_e32 v73, v108, v108
	v_add_f32_e32 v69, v69, v73
	v_add_f32_e32 v0, v69, v0
	v_mul_f32_e32 v69, v97, v97
	v_mul_f32_e32 v73, v99, v99
	v_fmac_f32_e32 v69, v96, v96
	v_fmac_f32_e32 v73, v98, v98
	v_add_f32_e32 v69, v69, v73
	v_add_f32_e32 v0, v69, v0
	v_mul_f32_e32 v69, v93, v93
	v_mul_f32_e32 v73, v95, v95
	v_fmac_f32_e32 v69, v92, v92
	v_fmac_f32_e32 v73, v94, v94
	v_add_f32_e32 v69, v69, v73
	v_add_f32_e32 v0, v69, v0
	v_mul_f32_e32 v69, v89, v89
	v_mul_f32_e32 v73, v91, v91
	v_fmac_f32_e32 v69, v88, v88
	v_fmac_f32_e32 v73, v90, v90
	v_add_f32_e32 v69, v69, v73
	v_add_f32_e32 v0, v69, v0
	v_mul_f32_e32 v69, v117, v117
	v_mul_f32_e32 v73, v113, v113
	v_fmac_f32_e32 v69, v116, v116
	v_fmac_f32_e32 v73, v112, v112
	v_add_f32_e32 v69, v69, v73
	v_add_f32_e32 v0, v69, v0
	v_mul_f32_e32 v69, v123, v123
	v_mul_f32_e32 v73, v119, v119
	v_fmac_f32_e32 v69, v122, v122
	v_fmac_f32_e32 v73, v118, v118
	v_add_f32_e32 v69, v69, v73
	v_add_f32_e32 v0, v69, v0
	v_mul_f32_e32 v69, v129, v129
	v_mul_f32_e32 v73, v125, v125
	v_fmac_f32_e32 v69, v128, v128
	v_fmac_f32_e32 v73, v124, v124
	v_pk_fma_f32 v[76:77], v[36:37], v[76:77], v[206:207]
	v_add_f32_e32 v69, v69, v73
	v_add_f32_e32 v0, v69, v0
	v_mul_f32_e32 v69, v133, v133
	v_mul_f32_e32 v73, v77, v77
	v_fmac_f32_e32 v69, v132, v132
	v_fmac_f32_e32 v73, v76, v76
	v_pk_fma_f32 v[74:75], v[40:41], v[74:75], v[218:219]
	v_pk_fma_f32 v[78:79], v[38:39], v[78:79], v[208:209]
	v_add_f32_e32 v69, v69, v73
	v_add_f32_e32 v0, v69, v0
	v_mul_f32_e32 v69, v79, v79
	v_mul_f32_e32 v73, v75, v75
	v_fmac_f32_e32 v69, v78, v78
	v_fmac_f32_e32 v73, v74, v74
	v_pk_fma_f32 v[82:83], v[46:47], v[82:83], v[220:221]
	v_add_f32_e32 v69, v69, v73
	v_add_f32_e32 v0, v69, v0
	v_mul_f32_e32 v69, v83, v83
	v_mul_f32_e32 v73, v81, v81
	v_fmac_f32_e32 v69, v82, v82
	v_fmac_f32_e32 v73, v80, v80
	v_pk_fma_f32 v[84:85], v[52:53], v[84:85], v[224:225]
	v_pk_fma_f32 v[86:87], v[50:51], v[86:87], v[222:223]
	v_add_f32_e32 v69, v69, v73
	v_add_f32_e32 v0, v69, v0
	v_mul_f32_e32 v69, v87, v87
	v_mul_f32_e32 v73, v85, v85
	v_fmac_f32_e32 v69, v86, v86
	v_fmac_f32_e32 v73, v84, v84
	v_pk_fma_f32 v[114:115], v[56:57], v[114:115], v[228:229]
	v_pk_fma_f32 v[120:121], v[54:55], v[120:121], v[226:227]
	v_add_f32_e32 v69, v69, v73
	v_add_f32_e32 v0, v69, v0
	v_mul_f32_e32 v69, v121, v121
	v_mul_f32_e32 v73, v115, v115
	v_fmac_f32_e32 v69, v120, v120
	v_fmac_f32_e32 v73, v114, v114
	v_pk_fma_f32 v[126:127], v[60:61], v[126:127], v[230:231]
	v_pk_fma_f32 v[130:131], v[58:59], v[130:131], v[200:201]
	v_add_f32_e32 v69, v69, v73
	v_add_f32_e32 v0, v69, v0
	v_mul_f32_e32 v69, v131, v131
	v_mul_f32_e32 v73, v127, v127
	v_fmac_f32_e32 v69, v130, v130
	v_fmac_f32_e32 v73, v126, v126
	v_pk_fma_f32 v[134:135], v[64:65], v[134:135], v[232:233]
	v_pk_fma_f32 v[136:137], v[62:63], v[136:137], v[202:203]
	v_add_f32_e32 v69, v69, v73
	v_add_f32_e32 v0, v69, v0
	v_mul_f32_e32 v69, v137, v137
	v_mul_f32_e32 v73, v135, v135
	v_fmac_f32_e32 v69, v136, v136
	v_fmac_f32_e32 v73, v134, v134
	v_add_f32_e32 v69, v69, v73
	v_add_f32_e32 v0, v69, v0
	ds_swizzle_b32 v69, v0 offset:swizzle(SWAP,1)
	v_cvt_pk_bf16_f32 v72, v132, v133
	v_cvt_pk_bf16_f32 v73, v76, v77
	global_store_dwordx2 v[70:71], v[72:73], off offset:512
	v_cvt_pk_bf16_f32 v72, v78, v79
	s_waitcnt lgkmcnt(0)
	v_add_f32_e32 v0, v0, v69
	ds_swizzle_b32 v69, v0 offset:swizzle(SWAP,2)
	v_cvt_pk_bf16_f32 v73, v74, v75
	global_store_dwordx2 v[70:71], v[72:73], off offset:1024
	v_cvt_pk_bf16_f32 v72, v82, v83
	v_cvt_pk_bf16_f32 v73, v80, v81
	s_waitcnt lgkmcnt(0)
	v_add_f32_e32 v0, v0, v69
	ds_swizzle_b32 v69, v0 offset:swizzle(SWAP,4)
	global_store_dwordx2 v[70:71], v[72:73], off offset:1536
	v_cvt_pk_bf16_f32 v72, v86, v87
	v_cvt_pk_bf16_f32 v73, v84, v85
	global_store_dwordx2 v[70:71], v[72:73], off offset:2048
	s_waitcnt lgkmcnt(0)
	v_add_f32_e32 v0, v0, v69
	ds_swizzle_b32 v69, v0 offset:swizzle(SWAP,8)
	v_cvt_pk_bf16_f32 v72, v120, v121
	v_cvt_pk_bf16_f32 v73, v114, v115
	global_store_dwordx2 v[70:71], v[72:73], off offset:2560
	v_cvt_pk_bf16_f32 v72, v130, v131
	s_waitcnt lgkmcnt(0)
	v_add_f32_e32 v0, v0, v69
	ds_swizzle_b32 v69, v0 offset:swizzle(SWAP,16)
	v_cvt_pk_bf16_f32 v73, v126, v127
	v_cmp_eq_u32_e32 vcc, 0, v68
	global_store_dwordx2 v[70:71], v[72:73], off offset:3072
	v_cvt_pk_bf16_f32 v72, v136, v137
	s_waitcnt lgkmcnt(0)
	v_add_f32_e32 v0, v0, v69
	v_cvt_pk_bf16_f32 v73, v134, v135
	global_store_dwordx2 v[70:71], v[72:73], off offset:3584
	v_readlane_b32 s0, v0, 0
	v_readlane_b32 s1, v0, 32
	s_and_saveexec_b64 s[4:5], vcc
	s_cbranch_execz .LBB0_1240
	v_mov_b32_e32 v0, s1
	v_add_f32_e32 v0, s0, v0
	v_fmamk_f32 v0, v0, 0x39800000, v211
	v_mul_f32_e32 v68, 0x4f800000, v0
	v_cmp_gt_f32_e32 vcc, s94, v0
	v_readlane_b32 s16, v252, 0
	v_readlane_b32 s18, v252, 2
	v_cndmask_b32_e32 v0, v0, v68, vcc
	v_sqrt_f32_e32 v68, v0
	v_readlane_b32 s19, v252, 3
	v_readlane_b32 s17, v252, 1
	v_add_u32_e32 v69, -1, v68
	v_fma_f32 v71, -v69, v68, v0
	v_add_u32_e32 v70, 1, v68
	v_cmp_ge_f32_e64 s[0:1], 0, v71
	s_nop 1
	v_cndmask_b32_e64 v69, v68, v69, s[0:1]
	v_fma_f32 v68, -v70, v68, v0
	v_cmp_lt_f32_e64 s[0:1], 0, v68
	s_nop 1
	v_cndmask_b32_e64 v68, v69, v70, s[0:1]
	v_mul_f32_e32 v69, 0x37800000, v68
	v_cndmask_b32_e32 v68, v68, v69, vcc
	v_cmp_class_f32_e32 vcc, v0, v212
	s_nop 1
	v_cndmask_b32_e32 v0, v68, v0, vcc
	v_div_scale_f32 v68, s[0:1], v0, v0, 1.0
	v_rcp_f32_e32 v69, v68
	s_add_u32 s0, s18, s8
	s_addc_u32 s1, s19, s9
	v_fma_f32 v70, -v68, v69, 1.0
	v_fmac_f32_e32 v69, v70, v69
	v_div_scale_f32 v70, vcc, 1.0, v0, 1.0
	v_mul_f32_e32 v71, v70, v69
	v_fma_f32 v72, -v68, v71, v70
	v_fmac_f32_e32 v71, v72, v69
	v_fma_f32 v68, -v68, v71, v70
	v_div_fmas_f32 v68, v68, v69, v71
	v_div_fixup_f32 v0, v68, v0, 1.0
	global_store_dword v1, v0, s[0:1]
	s_branch .LBB0_1240
